# barrier: non-leader WGs poll TOPGEN directly (no XGEN forwarding hop); on top of early inv
# speedup vs baseline: 1.0117x; 1.0018x over previous
; __device__ __forceinline__ unsigned xb_ld(unsigned* p)              { return __hip_atomic_load(p, __ATOMIC_RELAXED, __HIP_MEMORY_SCOPE_AGENT); }
; __device__ __forceinline__ unsigned xb_add(unsigned* p, unsigned v) { return __hip_atomic_fetch_add(p, v, __ATOMIC_RELAXED, __HIP_MEMORY_SCOPE_AGENT); }
; #define XB_SPIN(cond, bar) do { unsigned _sp = 0; while (cond) { __builtin_amdgcn_s_sleep(1); \
;     if ((++_sp & 255u) == 0u) { if (xb_ld(&(bar)[XB_TMO])) break; if (_sp > XB_SPIN_CAP) { atomicAdd(&(bar)[XB_TMO], 1u); break; } } } } while (0)
; __device__ __forceinline__ void xcd_barrier(const XcdBarrier& b) {
;     ...
;         const unsigned old = xb_add(&bar[XB_XSUB(b.x)], 1u);
;         const unsigned gen = old / nloc;
;         if (old + 1u == (gen + 1u) * nloc) {
;             __builtin_amdgcn_fence(__ATOMIC_RELEASE, "agent");
;             asm volatile("s_waitcnt vmcnt(0)" ::: "memory");
;             const unsigned og = xb_add(&bar[XB_TOP], 1u);
;             const unsigned tg = og / nx;
;             if (og + 1u == (tg + 1u) * nx) xb_add(&bar[XB_TOPGEN], 1u);
;             else XB_SPIN(xb_ld(&bar[XB_TOPGEN]) == tg, bar);
;             __builtin_amdgcn_fence(__ATOMIC_ACQUIRE, "agent");
;             xb_add(&bar[XB_XGEN(b.x)], 1u);
;             asm volatile("s_waitcnt vmcnt(0)" ::: "memory");
;         } else {
;             XB_SPIN(xb_ld(&bar[XB_XGEN(b.x)]) == gen, bar);
.LBB0_31:
	s_or_b64 exec, exec, s[10:11]
	v_cvt_f32_u32_e32 v5, v3
	s_waitcnt vmcnt(0)
	v_readfirstlane_b32 s8, v4
	v_sub_u32_e32 v4, 0, v3
	v_rcp_iflag_f32_e32 v5, v5
	v_add_u32_e32 v6, s8, v2
	v_mul_f32_e32 v5, 0x4f7ffffe, v5
	v_cvt_u32_f32_e32 v5, v5
	v_mul_lo_u32 v2, v4, v5
	v_mul_hi_u32 v2, v5, v2
	v_add_u32_e32 v2, v5, v2
	v_mul_hi_u32 v2, v6, v2
	v_mul_lo_u32 v4, v2, v3
	v_sub_u32_e32 v4, v6, v4
	v_add_u32_e32 v5, 1, v2
	v_cmp_ge_u32_e32 vcc, v4, v3
	s_nop 1
	v_cndmask_b32_e32 v2, v2, v5, vcc
	v_sub_u32_e32 v5, v4, v3
	v_cndmask_b32_e32 v4, v4, v5, vcc
	v_add_u32_e32 v5, 1, v2
	v_cmp_ge_u32_e32 vcc, v4, v3
	v_add_u32_e32 v4, 1, v6
	s_nop 0
	v_cndmask_b32_e32 v2, v2, v5, vcc
	v_mul_lo_u32 v5, v3, v2
	v_add_u32_e32 v3, v5, v3
	v_cmp_ne_u32_e32 vcc, v4, v3
	s_and_saveexec_b64 s[8:9], vcc
	s_xor_b64 s[8:9], exec, s[8:9]
	s_cbranch_execz .LBB0_45
	s_waitcnt lgkmcnt(0)
	buffer_inv sc1
	s_add_u32 s16, s60, 0x7500
	s_addc_u32 s17, s61, 0
	v_mov_b32_e32 v1, 0
	global_load_dword v1, v1, s[16:17] sc1
	s_waitcnt vmcnt(0)
	v_cmp_eq_u32_e32 vcc, v1, v2
	s_and_saveexec_b64 s[10:11], vcc
	s_cbranch_execz .LBB0_44
	s_add_u32 s12, s60, 0x4200
	s_addc_u32 s13, s61, 0
	s_mov_b32 s14, 1
	s_mov_b64 s[18:19], 0
	v_mov_b32_e32 v1, 0
	s_branch .LBB0_35

; __device__ __forceinline__ unsigned xb_add(unsigned* p, unsigned v) { return __hip_atomic_fetch_add(p, v, __ATOMIC_RELAXED, __HIP_MEMORY_SCOPE_AGENT); }
; __device__ __forceinline__ void xcd_barrier(const XcdBarrier& b) {
;     ...
;             __builtin_amdgcn_fence(__ATOMIC_ACQUIRE, "agent");
;             xb_add(&bar[XB_XGEN(b.x)], 1u);
;             asm volatile("s_waitcnt vmcnt(0)" ::: "memory");
.LBB0_62:
	s_or_b64 exec, exec, s[8:9]
	s_mov_b64 s[8:9], exec
	v_mbcnt_lo_u32_b32 v1, s8, 0
	v_mbcnt_hi_u32_b32 v1, s9, v1
	v_cmp_eq_u32_e32 vcc, 0, v1
	s_and_saveexec_b64 s[10:11], vcc
	s_cbranch_execz .LBB0_64
	s_bcnt1_i32_b64 s8, s[8:9]
	v_mov_b32_e32 v1, 0x2000
	v_mov_b32_e32 v2, s8
.LBB0_64:
	s_or_b64 exec, exec, s[10:11]
	s_waitcnt vmcnt(0)

; __device__ __forceinline__ unsigned xb_ld(unsigned* p)              { return __hip_atomic_load(p, __ATOMIC_RELAXED, __HIP_MEMORY_SCOPE_AGENT); }
; __device__ __forceinline__ unsigned xb_add(unsigned* p, unsigned v) { return __hip_atomic_fetch_add(p, v, __ATOMIC_RELAXED, __HIP_MEMORY_SCOPE_AGENT); }
; #define XB_SPIN(cond, bar) do { unsigned _sp = 0; while (cond) { __builtin_amdgcn_s_sleep(1); \
;     if ((++_sp & 255u) == 0u) { if (xb_ld(&(bar)[XB_TMO])) break; if (_sp > XB_SPIN_CAP) { atomicAdd(&(bar)[XB_TMO], 1u); break; } } } } while (0)
; __device__ __forceinline__ void xcd_barrier(const XcdBarrier& b) {
;     ...
;         const unsigned old = xb_add(&bar[XB_XSUB(b.x)], 1u);
;         const unsigned gen = old / nloc;
;         if (old + 1u == (gen + 1u) * nloc) {
;             __builtin_amdgcn_fence(__ATOMIC_RELEASE, "agent");
;             asm volatile("s_waitcnt vmcnt(0)" ::: "memory");
;             const unsigned og = xb_add(&bar[XB_TOP], 1u);
;             const unsigned tg = og / nx;
;             if (og + 1u == (tg + 1u) * nx) xb_add(&bar[XB_TOPGEN], 1u);
;             else XB_SPIN(xb_ld(&bar[XB_TOPGEN]) == tg, bar);
;             __builtin_amdgcn_fence(__ATOMIC_ACQUIRE, "agent");
;             xb_add(&bar[XB_XGEN(b.x)], 1u);
;             asm volatile("s_waitcnt vmcnt(0)" ::: "memory");
;         } else {
;             XB_SPIN(xb_ld(&bar[XB_XGEN(b.x)]) == gen, bar);
.LBB0_119:
	s_or_b64 exec, exec, s[8:9]
	v_cvt_f32_u32_e32 v5, v3
	s_waitcnt vmcnt(0)
	v_readfirstlane_b32 s3, v4
	v_sub_u32_e32 v4, 0, v3
	v_rcp_iflag_f32_e32 v5, v5
	v_add_u32_e32 v6, s3, v2
	v_mul_f32_e32 v5, 0x4f7ffffe, v5
	v_cvt_u32_f32_e32 v5, v5
	v_mul_lo_u32 v2, v4, v5
	v_mul_hi_u32 v2, v5, v2
	v_add_u32_e32 v2, v5, v2
	v_mul_hi_u32 v2, v6, v2
	v_mul_lo_u32 v4, v2, v3
	v_sub_u32_e32 v4, v6, v4
	v_add_u32_e32 v5, 1, v2
	v_cmp_ge_u32_e32 vcc, v4, v3
	s_nop 1
	v_cndmask_b32_e32 v2, v2, v5, vcc
	v_sub_u32_e32 v5, v4, v3
	v_cndmask_b32_e32 v4, v4, v5, vcc
	v_add_u32_e32 v5, 1, v2
	v_cmp_ge_u32_e32 vcc, v4, v3
	v_add_u32_e32 v4, 1, v6
	s_nop 0
	v_cndmask_b32_e32 v2, v2, v5, vcc
	v_mul_lo_u32 v5, v3, v2
	v_add_u32_e32 v3, v5, v3
	v_cmp_ne_u32_e32 vcc, v4, v3
	s_and_saveexec_b64 s[6:7], vcc
	s_xor_b64 s[6:7], exec, s[6:7]
	s_cbranch_execz .LBB0_133
	s_waitcnt lgkmcnt(0)
	buffer_inv sc1
	s_add_u32 s12, s60, 0x7500
	s_addc_u32 s13, s61, 0
	v_mov_b32_e32 v1, 0
	global_load_dword v1, v1, s[12:13] sc1
	s_waitcnt vmcnt(0)
	v_cmp_eq_u32_e32 vcc, v1, v2
	s_and_saveexec_b64 s[8:9], vcc
	s_cbranch_execz .LBB0_132
	s_add_u32 s10, s60, 0x4200
	s_addc_u32 s11, s61, 0
	s_mov_b32 s3, 1
	s_mov_b64 s[16:17], 0
	v_mov_b32_e32 v1, 0
	s_branch .LBB0_123

; __device__ __forceinline__ unsigned xb_add(unsigned* p, unsigned v) { return __hip_atomic_fetch_add(p, v, __ATOMIC_RELAXED, __HIP_MEMORY_SCOPE_AGENT); }
; __device__ __forceinline__ void xcd_barrier(const XcdBarrier& b) {
;     ...
;             __builtin_amdgcn_fence(__ATOMIC_ACQUIRE, "agent");
;             xb_add(&bar[XB_XGEN(b.x)], 1u);
;             asm volatile("s_waitcnt vmcnt(0)" ::: "memory");
.LBB0_150:
	s_or_b64 exec, exec, s[6:7]
	s_mov_b64 s[6:7], exec
	v_mbcnt_lo_u32_b32 v1, s6, 0
	v_mbcnt_hi_u32_b32 v1, s7, v1
	v_cmp_eq_u32_e32 vcc, 0, v1
	s_and_saveexec_b64 s[8:9], vcc
	s_cbranch_execz .LBB0_152
	s_bcnt1_i32_b64 s3, s[6:7]
	v_mov_b32_e32 v1, 0x2000
	v_mov_b32_e32 v2, s3
.LBB0_152:
	s_or_b64 exec, exec, s[8:9]
	s_waitcnt vmcnt(0)

; __device__ __forceinline__ unsigned xb_ld(unsigned* p)              { return __hip_atomic_load(p, __ATOMIC_RELAXED, __HIP_MEMORY_SCOPE_AGENT); }
; __device__ __forceinline__ unsigned xb_add(unsigned* p, unsigned v) { return __hip_atomic_fetch_add(p, v, __ATOMIC_RELAXED, __HIP_MEMORY_SCOPE_AGENT); }
; #define XB_SPIN(cond, bar) do { unsigned _sp = 0; while (cond) { __builtin_amdgcn_s_sleep(1); \
;     if ((++_sp & 255u) == 0u) { if (xb_ld(&(bar)[XB_TMO])) break; if (_sp > XB_SPIN_CAP) { atomicAdd(&(bar)[XB_TMO], 1u); break; } } } } while (0)
; __device__ __forceinline__ void xcd_barrier(const XcdBarrier& b) {
;     ...
;         const unsigned old = xb_add(&bar[XB_XSUB(b.x)], 1u);
;         const unsigned gen = old / nloc;
;         if (old + 1u == (gen + 1u) * nloc) {
;             __builtin_amdgcn_fence(__ATOMIC_RELEASE, "agent");
;             asm volatile("s_waitcnt vmcnt(0)" ::: "memory");
;             const unsigned og = xb_add(&bar[XB_TOP], 1u);
;             const unsigned tg = og / nx;
;             if (og + 1u == (tg + 1u) * nx) xb_add(&bar[XB_TOPGEN], 1u);
;             else XB_SPIN(xb_ld(&bar[XB_TOPGEN]) == tg, bar);
;             __builtin_amdgcn_fence(__ATOMIC_ACQUIRE, "agent");
;             xb_add(&bar[XB_XGEN(b.x)], 1u);
;             asm volatile("s_waitcnt vmcnt(0)" ::: "memory");
;         } else {
;             XB_SPIN(xb_ld(&bar[XB_XGEN(b.x)]) == gen, bar);
.LBB0_191:
	s_or_b64 exec, exec, s[6:7]
	v_cvt_f32_u32_e32 v5, v3
	s_waitcnt vmcnt(0)
	v_readfirstlane_b32 s4, v4
	v_sub_u32_e32 v4, 0, v3
	v_rcp_iflag_f32_e32 v5, v5
	v_add_u32_e32 v6, s4, v2
	v_mul_f32_e32 v5, 0x4f7ffffe, v5
	v_cvt_u32_f32_e32 v5, v5
	v_mul_lo_u32 v2, v4, v5
	v_mul_hi_u32 v2, v5, v2
	v_add_u32_e32 v2, v5, v2
	v_mul_hi_u32 v2, v6, v2
	v_mul_lo_u32 v4, v2, v3
	v_sub_u32_e32 v4, v6, v4
	v_add_u32_e32 v5, 1, v2
	v_cmp_ge_u32_e32 vcc, v4, v3
	s_nop 1
	v_cndmask_b32_e32 v2, v2, v5, vcc
	v_sub_u32_e32 v5, v4, v3
	v_cndmask_b32_e32 v4, v4, v5, vcc
	v_add_u32_e32 v5, 1, v2
	v_cmp_ge_u32_e32 vcc, v4, v3
	v_add_u32_e32 v4, 1, v6
	s_nop 0
	v_cndmask_b32_e32 v2, v2, v5, vcc
	v_mul_lo_u32 v5, v3, v2
	v_add_u32_e32 v3, v5, v3
	v_cmp_ne_u32_e32 vcc, v4, v3
	s_and_saveexec_b64 s[4:5], vcc
	s_xor_b64 s[4:5], exec, s[4:5]
	s_cbranch_execz .LBB0_205
	s_waitcnt lgkmcnt(0)
	buffer_inv sc1
	s_add_u32 s8, s34, 0x3500
	s_addc_u32 s9, s35, 0
	v_mov_b32_e32 v1, 0
	global_load_dword v1, v1, s[8:9] sc1
	s_waitcnt vmcnt(0)
	v_cmp_eq_u32_e32 vcc, v1, v2
	s_and_saveexec_b64 s[6:7], vcc
	s_cbranch_execz .LBB0_204
	s_mov_b32 s14, 1
	s_mov_b64 s[10:11], 0
	v_mov_b32_e32 v1, 0
	s_branch .LBB0_195

; __device__ __forceinline__ unsigned xb_add(unsigned* p, unsigned v) { return __hip_atomic_fetch_add(p, v, __ATOMIC_RELAXED, __HIP_MEMORY_SCOPE_AGENT); }
; __device__ __forceinline__ void xcd_barrier(const XcdBarrier& b) {
;     ...
;             __builtin_amdgcn_fence(__ATOMIC_ACQUIRE, "agent");
;             xb_add(&bar[XB_XGEN(b.x)], 1u);
;             asm volatile("s_waitcnt vmcnt(0)" ::: "memory");
.LBB0_222:
	s_or_b64 exec, exec, s[6:7]
	s_mov_b64 s[6:7], exec
	v_mbcnt_lo_u32_b32 v1, s6, 0
	v_mbcnt_hi_u32_b32 v1, s7, v1
	v_cmp_eq_u32_e32 vcc, 0, v1
	s_and_saveexec_b64 s[8:9], vcc
	s_cbranch_execz .LBB0_224
	s_bcnt1_i32_b64 s6, s[6:7]
	v_mov_b32_e32 v1, 0x2000
	v_mov_b32_e32 v2, s6
.LBB0_224:
	s_or_b64 exec, exec, s[8:9]
	s_waitcnt vmcnt(0)

; __device__ __forceinline__ unsigned xb_ld(unsigned* p)              { return __hip_atomic_load(p, __ATOMIC_RELAXED, __HIP_MEMORY_SCOPE_AGENT); }
; __device__ __forceinline__ unsigned xb_add(unsigned* p, unsigned v) { return __hip_atomic_fetch_add(p, v, __ATOMIC_RELAXED, __HIP_MEMORY_SCOPE_AGENT); }
; #define XB_SPIN(cond, bar) do { unsigned _sp = 0; while (cond) { __builtin_amdgcn_s_sleep(1); \
;     if ((++_sp & 255u) == 0u) { if (xb_ld(&(bar)[XB_TMO])) break; if (_sp > XB_SPIN_CAP) { atomicAdd(&(bar)[XB_TMO], 1u); break; } } } } while (0)
; __device__ __forceinline__ void xcd_barrier(const XcdBarrier& b) {
;     ...
;         const unsigned old = xb_add(&bar[XB_XSUB(b.x)], 1u);
;         const unsigned gen = old / nloc;
;         if (old + 1u == (gen + 1u) * nloc) {
;             __builtin_amdgcn_fence(__ATOMIC_RELEASE, "agent");
;             asm volatile("s_waitcnt vmcnt(0)" ::: "memory");
;             const unsigned og = xb_add(&bar[XB_TOP], 1u);
;             const unsigned tg = og / nx;
;             if (og + 1u == (tg + 1u) * nx) xb_add(&bar[XB_TOPGEN], 1u);
;             else XB_SPIN(xb_ld(&bar[XB_TOPGEN]) == tg, bar);
;             __builtin_amdgcn_fence(__ATOMIC_ACQUIRE, "agent");
;             xb_add(&bar[XB_XGEN(b.x)], 1u);
;             asm volatile("s_waitcnt vmcnt(0)" ::: "memory");
;         } else {
;             XB_SPIN(xb_ld(&bar[XB_XGEN(b.x)]) == gen, bar);
.LBB0_401:
	s_or_b64 exec, exec, s[8:9]
	v_cvt_f32_u32_e32 v5, v3
	s_waitcnt vmcnt(0)
	v_readfirstlane_b32 s6, v4
	v_sub_u32_e32 v4, 0, v3
	v_rcp_iflag_f32_e32 v5, v5
	v_add_u32_e32 v6, s6, v2
	v_mul_f32_e32 v5, 0x4f7ffffe, v5
	v_cvt_u32_f32_e32 v5, v5
	v_mul_lo_u32 v2, v4, v5
	v_mul_hi_u32 v2, v5, v2
	v_add_u32_e32 v2, v5, v2
	v_mul_hi_u32 v2, v6, v2
	v_mul_lo_u32 v4, v2, v3
	v_sub_u32_e32 v4, v6, v4
	v_add_u32_e32 v5, 1, v2
	v_cmp_ge_u32_e32 vcc, v4, v3
	s_nop 1
	v_cndmask_b32_e32 v2, v2, v5, vcc
	v_sub_u32_e32 v5, v4, v3
	v_cndmask_b32_e32 v4, v4, v5, vcc
	v_add_u32_e32 v5, 1, v2
	v_cmp_ge_u32_e32 vcc, v4, v3
	v_add_u32_e32 v4, 1, v6
	s_nop 0
	v_cndmask_b32_e32 v2, v2, v5, vcc
	v_mul_lo_u32 v5, v3, v2
	v_add_u32_e32 v3, v5, v3
	v_cmp_ne_u32_e32 vcc, v4, v3
	s_and_saveexec_b64 s[6:7], vcc
	s_xor_b64 s[6:7], exec, s[6:7]
	s_cbranch_execz .LBB0_415
	s_waitcnt lgkmcnt(0)
	buffer_inv sc1
	s_add_u32 s10, s34, 0x3500
	s_addc_u32 s11, s35, 0
	v_mov_b32_e32 v1, 0
	global_load_dword v1, v1, s[10:11] sc1
	s_waitcnt vmcnt(0)
	v_cmp_eq_u32_e32 vcc, v1, v2
	s_and_saveexec_b64 s[8:9], vcc
	s_cbranch_execz .LBB0_414
	s_mov_b32 s14, 1
	s_mov_b64 s[12:13], 0
	v_mov_b32_e32 v1, 0
	s_branch .LBB0_405

; __device__ __forceinline__ unsigned xb_add(unsigned* p, unsigned v) { return __hip_atomic_fetch_add(p, v, __ATOMIC_RELAXED, __HIP_MEMORY_SCOPE_AGENT); }
; __device__ __forceinline__ void xcd_barrier(const XcdBarrier& b) {
;     ...
;             __builtin_amdgcn_fence(__ATOMIC_ACQUIRE, "agent");
;             xb_add(&bar[XB_XGEN(b.x)], 1u);
;             asm volatile("s_waitcnt vmcnt(0)" ::: "memory");
.LBB0_432:
	s_or_b64 exec, exec, s[6:7]
	s_mov_b64 s[6:7], exec
	v_mbcnt_lo_u32_b32 v1, s6, 0
	v_mbcnt_hi_u32_b32 v1, s7, v1
	v_cmp_eq_u32_e32 vcc, 0, v1
	s_and_saveexec_b64 s[8:9], vcc
	s_cbranch_execz .LBB0_434
	s_bcnt1_i32_b64 s6, s[6:7]
	v_mov_b32_e32 v1, 0x2000
	v_mov_b32_e32 v2, s6
.LBB0_434:
	s_or_b64 exec, exec, s[8:9]
	s_waitcnt vmcnt(0)

; __device__ __forceinline__ unsigned xb_ld(unsigned* p)              { return __hip_atomic_load(p, __ATOMIC_RELAXED, __HIP_MEMORY_SCOPE_AGENT); }
; __device__ __forceinline__ unsigned xb_add(unsigned* p, unsigned v) { return __hip_atomic_fetch_add(p, v, __ATOMIC_RELAXED, __HIP_MEMORY_SCOPE_AGENT); }
; #define XB_SPIN(cond, bar) do { unsigned _sp = 0; while (cond) { __builtin_amdgcn_s_sleep(1); \
;     if ((++_sp & 255u) == 0u) { if (xb_ld(&(bar)[XB_TMO])) break; if (_sp > XB_SPIN_CAP) { atomicAdd(&(bar)[XB_TMO], 1u); break; } } } } while (0)
; __device__ __forceinline__ void xcd_barrier(const XcdBarrier& b) {
;     ...
;         const unsigned old = xb_add(&bar[XB_XSUB(b.x)], 1u);
;         const unsigned gen = old / nloc;
;         if (old + 1u == (gen + 1u) * nloc) {
;             __builtin_amdgcn_fence(__ATOMIC_RELEASE, "agent");
;             asm volatile("s_waitcnt vmcnt(0)" ::: "memory");
;             const unsigned og = xb_add(&bar[XB_TOP], 1u);
;             const unsigned tg = og / nx;
;             if (og + 1u == (tg + 1u) * nx) xb_add(&bar[XB_TOPGEN], 1u);
;             else XB_SPIN(xb_ld(&bar[XB_TOPGEN]) == tg, bar);
;             __builtin_amdgcn_fence(__ATOMIC_ACQUIRE, "agent");
;             xb_add(&bar[XB_XGEN(b.x)], 1u);
;             asm volatile("s_waitcnt vmcnt(0)" ::: "memory");
;         } else {
;             XB_SPIN(xb_ld(&bar[XB_XGEN(b.x)]) == gen, bar);
.LBB0_475:
	s_or_b64 exec, exec, s[6:7]
	v_cvt_f32_u32_e32 v5, v3
	s_waitcnt vmcnt(0)
	v_readfirstlane_b32 s4, v4
	v_sub_u32_e32 v4, 0, v3
	v_rcp_iflag_f32_e32 v5, v5
	v_add_u32_e32 v6, s4, v2
	v_mul_f32_e32 v5, 0x4f7ffffe, v5
	v_cvt_u32_f32_e32 v5, v5
	v_mul_lo_u32 v2, v4, v5
	v_mul_hi_u32 v2, v5, v2
	v_add_u32_e32 v2, v5, v2
	v_mul_hi_u32 v2, v6, v2
	v_mul_lo_u32 v4, v2, v3
	v_sub_u32_e32 v4, v6, v4
	v_add_u32_e32 v5, 1, v2
	v_cmp_ge_u32_e32 vcc, v4, v3
	s_nop 1
	v_cndmask_b32_e32 v2, v2, v5, vcc
	v_sub_u32_e32 v5, v4, v3
	v_cndmask_b32_e32 v4, v4, v5, vcc
	v_add_u32_e32 v5, 1, v2
	v_cmp_ge_u32_e32 vcc, v4, v3
	v_add_u32_e32 v4, 1, v6
	s_nop 0
	v_cndmask_b32_e32 v2, v2, v5, vcc
	v_mul_lo_u32 v5, v3, v2
	v_add_u32_e32 v3, v5, v3
	v_cmp_ne_u32_e32 vcc, v4, v3
	s_and_saveexec_b64 s[4:5], vcc
	s_xor_b64 s[4:5], exec, s[4:5]
	s_cbranch_execz .LBB0_489
	s_waitcnt lgkmcnt(0)
	buffer_inv sc1
	s_add_u32 s8, s34, 0x3500
	s_addc_u32 s9, s35, 0
	v_mov_b32_e32 v1, 0
	global_load_dword v1, v1, s[8:9] sc1
	s_waitcnt vmcnt(0)
	v_cmp_eq_u32_e32 vcc, v1, v2
	s_and_saveexec_b64 s[6:7], vcc
	s_cbranch_execz .LBB0_488
	s_mov_b32 s11, 1
	s_mov_b64 s[22:23], 0
	v_mov_b32_e32 v1, 0
	s_branch .LBB0_479

; __device__ __forceinline__ unsigned xb_add(unsigned* p, unsigned v) { return __hip_atomic_fetch_add(p, v, __ATOMIC_RELAXED, __HIP_MEMORY_SCOPE_AGENT); }
; __device__ __forceinline__ void xcd_barrier(const XcdBarrier& b) {
;     ...
;             __builtin_amdgcn_fence(__ATOMIC_ACQUIRE, "agent");
;             xb_add(&bar[XB_XGEN(b.x)], 1u);
;             asm volatile("s_waitcnt vmcnt(0)" ::: "memory");
.LBB0_506:
	s_or_b64 exec, exec, s[6:7]
	s_mov_b64 s[6:7], exec
	v_mbcnt_lo_u32_b32 v1, s6, 0
	v_mbcnt_hi_u32_b32 v1, s7, v1
	v_cmp_eq_u32_e32 vcc, 0, v1
	s_and_saveexec_b64 s[8:9], vcc
	s_cbranch_execz .LBB0_508
	s_bcnt1_i32_b64 s6, s[6:7]
	v_mov_b32_e32 v1, 0x2000
	v_mov_b32_e32 v2, s6
.LBB0_508:
	s_or_b64 exec, exec, s[8:9]
	s_waitcnt vmcnt(0)

; __device__ __forceinline__ unsigned xb_ld(unsigned* p)              { return __hip_atomic_load(p, __ATOMIC_RELAXED, __HIP_MEMORY_SCOPE_AGENT); }
; __device__ __forceinline__ unsigned xb_add(unsigned* p, unsigned v) { return __hip_atomic_fetch_add(p, v, __ATOMIC_RELAXED, __HIP_MEMORY_SCOPE_AGENT); }
; #define XB_SPIN(cond, bar) do { unsigned _sp = 0; while (cond) { __builtin_amdgcn_s_sleep(1); \
;     if ((++_sp & 255u) == 0u) { if (xb_ld(&(bar)[XB_TMO])) break; if (_sp > XB_SPIN_CAP) { atomicAdd(&(bar)[XB_TMO], 1u); break; } } } } while (0)
; __device__ __forceinline__ void xcd_barrier(const XcdBarrier& b) {
;     ...
;         const unsigned old = xb_add(&bar[XB_XSUB(b.x)], 1u);
;         const unsigned gen = old / nloc;
;         if (old + 1u == (gen + 1u) * nloc) {
;             __builtin_amdgcn_fence(__ATOMIC_RELEASE, "agent");
;             asm volatile("s_waitcnt vmcnt(0)" ::: "memory");
;             const unsigned og = xb_add(&bar[XB_TOP], 1u);
;             const unsigned tg = og / nx;
;             if (og + 1u == (tg + 1u) * nx) xb_add(&bar[XB_TOPGEN], 1u);
;             else XB_SPIN(xb_ld(&bar[XB_TOPGEN]) == tg, bar);
;             __builtin_amdgcn_fence(__ATOMIC_ACQUIRE, "agent");
;             xb_add(&bar[XB_XGEN(b.x)], 1u);
;             asm volatile("s_waitcnt vmcnt(0)" ::: "memory");
;         } else {
;             XB_SPIN(xb_ld(&bar[XB_XGEN(b.x)]) == gen, bar);
.LBB0_580:
	s_or_b64 exec, exec, s[6:7]
	v_cvt_f32_u32_e32 v5, v3
	s_waitcnt vmcnt(0)
	v_readfirstlane_b32 s4, v4
	v_sub_u32_e32 v4, 0, v3
	v_rcp_iflag_f32_e32 v5, v5
	v_add_u32_e32 v6, s4, v2
	v_mul_f32_e32 v5, 0x4f7ffffe, v5
	v_cvt_u32_f32_e32 v5, v5
	v_mul_lo_u32 v2, v4, v5
	v_mul_hi_u32 v2, v5, v2
	v_add_u32_e32 v2, v5, v2
	v_mul_hi_u32 v2, v6, v2
	v_mul_lo_u32 v4, v2, v3
	v_sub_u32_e32 v4, v6, v4
	v_add_u32_e32 v5, 1, v2
	v_cmp_ge_u32_e32 vcc, v4, v3
	s_nop 1
	v_cndmask_b32_e32 v2, v2, v5, vcc
	v_sub_u32_e32 v5, v4, v3
	v_cndmask_b32_e32 v4, v4, v5, vcc
	v_add_u32_e32 v5, 1, v2
	v_cmp_ge_u32_e32 vcc, v4, v3
	v_add_u32_e32 v4, 1, v6
	s_nop 0
	v_cndmask_b32_e32 v2, v2, v5, vcc
	v_mul_lo_u32 v5, v3, v2
	v_add_u32_e32 v3, v5, v3
	v_cmp_ne_u32_e32 vcc, v4, v3
	s_and_saveexec_b64 s[4:5], vcc
	s_xor_b64 s[4:5], exec, s[4:5]
	s_cbranch_execz .LBB0_594
	s_waitcnt lgkmcnt(0)
	buffer_inv sc1
	s_add_u32 s8, s34, 0x3500
	s_addc_u32 s9, s35, 0
	v_mov_b32_e32 v1, 0
	global_load_dword v1, v1, s[8:9] sc1
	s_waitcnt vmcnt(0)
	v_cmp_eq_u32_e32 vcc, v1, v2
	s_and_saveexec_b64 s[6:7], vcc
	s_cbranch_execz .LBB0_593
	s_mov_b32 s11, 1
	s_mov_b64 s[20:21], 0
	v_mov_b32_e32 v1, 0
	s_branch .LBB0_584

; __device__ __forceinline__ unsigned xb_add(unsigned* p, unsigned v) { return __hip_atomic_fetch_add(p, v, __ATOMIC_RELAXED, __HIP_MEMORY_SCOPE_AGENT); }
; __device__ __forceinline__ void xcd_barrier(const XcdBarrier& b) {
;     ...
;             __builtin_amdgcn_fence(__ATOMIC_ACQUIRE, "agent");
;             xb_add(&bar[XB_XGEN(b.x)], 1u);
;             asm volatile("s_waitcnt vmcnt(0)" ::: "memory");
.LBB0_611:
	s_or_b64 exec, exec, s[6:7]
	s_mov_b64 s[6:7], exec
	v_mbcnt_lo_u32_b32 v1, s6, 0
	v_mbcnt_hi_u32_b32 v1, s7, v1
	v_cmp_eq_u32_e32 vcc, 0, v1
	s_and_saveexec_b64 s[8:9], vcc
	s_cbranch_execz .LBB0_613
	s_bcnt1_i32_b64 s6, s[6:7]
	v_mov_b32_e32 v1, 0x2000
	v_mov_b32_e32 v2, s6
.LBB0_613:
	s_or_b64 exec, exec, s[8:9]
	s_waitcnt vmcnt(0)

; __device__ __forceinline__ unsigned xb_ld(unsigned* p)              { return __hip_atomic_load(p, __ATOMIC_RELAXED, __HIP_MEMORY_SCOPE_AGENT); }
; __device__ __forceinline__ unsigned xb_add(unsigned* p, unsigned v) { return __hip_atomic_fetch_add(p, v, __ATOMIC_RELAXED, __HIP_MEMORY_SCOPE_AGENT); }
; #define XB_SPIN(cond, bar) do { unsigned _sp = 0; while (cond) { __builtin_amdgcn_s_sleep(1); \
;     if ((++_sp & 255u) == 0u) { if (xb_ld(&(bar)[XB_TMO])) break; if (_sp > XB_SPIN_CAP) { atomicAdd(&(bar)[XB_TMO], 1u); break; } } } } while (0)
; __device__ __forceinline__ void xcd_barrier(const XcdBarrier& b) {
;     ...
;         const unsigned old = xb_add(&bar[XB_XSUB(b.x)], 1u);
;         const unsigned gen = old / nloc;
;         if (old + 1u == (gen + 1u) * nloc) {
;             __builtin_amdgcn_fence(__ATOMIC_RELEASE, "agent");
;             asm volatile("s_waitcnt vmcnt(0)" ::: "memory");
;             const unsigned og = xb_add(&bar[XB_TOP], 1u);
;             const unsigned tg = og / nx;
;             if (og + 1u == (tg + 1u) * nx) xb_add(&bar[XB_TOPGEN], 1u);
;             else XB_SPIN(xb_ld(&bar[XB_TOPGEN]) == tg, bar);
;             __builtin_amdgcn_fence(__ATOMIC_ACQUIRE, "agent");
;             xb_add(&bar[XB_XGEN(b.x)], 1u);
;             asm volatile("s_waitcnt vmcnt(0)" ::: "memory");
;         } else {
;             XB_SPIN(xb_ld(&bar[XB_XGEN(b.x)]) == gen, bar);
.LBB0_656:
	s_or_b64 exec, exec, s[6:7]
	v_cvt_f32_u32_e32 v5, v3
	s_waitcnt vmcnt(0)
	v_readfirstlane_b32 s4, v4
	v_sub_u32_e32 v4, 0, v3
	v_rcp_iflag_f32_e32 v5, v5
	v_add_u32_e32 v6, s4, v2
	v_mul_f32_e32 v5, 0x4f7ffffe, v5
	v_cvt_u32_f32_e32 v5, v5
	v_mul_lo_u32 v2, v4, v5
	v_mul_hi_u32 v2, v5, v2
	v_add_u32_e32 v2, v5, v2
	v_mul_hi_u32 v2, v6, v2
	v_mul_lo_u32 v4, v2, v3
	v_sub_u32_e32 v4, v6, v4
	v_add_u32_e32 v5, 1, v2
	v_cmp_ge_u32_e32 vcc, v4, v3
	s_nop 1
	v_cndmask_b32_e32 v2, v2, v5, vcc
	v_sub_u32_e32 v5, v4, v3
	v_cndmask_b32_e32 v4, v4, v5, vcc
	v_add_u32_e32 v5, 1, v2
	v_cmp_ge_u32_e32 vcc, v4, v3
	v_add_u32_e32 v4, 1, v6
	s_nop 0
	v_cndmask_b32_e32 v2, v2, v5, vcc
	v_mul_lo_u32 v5, v3, v2
	v_add_u32_e32 v3, v5, v3
	v_cmp_ne_u32_e32 vcc, v4, v3
	s_and_saveexec_b64 s[4:5], vcc
	s_xor_b64 s[4:5], exec, s[4:5]
	s_cbranch_execz .LBB0_670
	s_waitcnt lgkmcnt(0)
	buffer_inv sc1
	s_add_u32 s8, s34, 0x3500
	s_addc_u32 s9, s35, 0
	v_mov_b32_e32 v1, 0
	global_load_dword v1, v1, s[8:9] sc1
	s_waitcnt vmcnt(0)
	v_cmp_eq_u32_e32 vcc, v1, v2
	s_and_saveexec_b64 s[6:7], vcc
	s_cbranch_execz .LBB0_669
	s_mov_b32 s11, 1
	s_mov_b64 s[14:15], 0
	v_mov_b32_e32 v1, 0
	s_branch .LBB0_660

; __device__ __forceinline__ unsigned xb_add(unsigned* p, unsigned v) { return __hip_atomic_fetch_add(p, v, __ATOMIC_RELAXED, __HIP_MEMORY_SCOPE_AGENT); }
; __device__ __forceinline__ void xcd_barrier(const XcdBarrier& b) {
;     ...
;             __builtin_amdgcn_fence(__ATOMIC_ACQUIRE, "agent");
;             xb_add(&bar[XB_XGEN(b.x)], 1u);
;             asm volatile("s_waitcnt vmcnt(0)" ::: "memory");
.LBB0_687:
	s_or_b64 exec, exec, s[4:5]
	s_mov_b64 s[4:5], exec
	v_mbcnt_lo_u32_b32 v1, s4, 0
	v_mbcnt_hi_u32_b32 v1, s5, v1
	v_cmp_eq_u32_e32 vcc, 0, v1
	s_and_saveexec_b64 s[6:7], vcc
	s_cbranch_execz .LBB0_689
	s_bcnt1_i32_b64 s4, s[4:5]
	v_mov_b32_e32 v1, 0x2000
	v_mov_b32_e32 v2, s4
.LBB0_689:
	s_or_b64 exec, exec, s[6:7]
	s_waitcnt vmcnt(0)
